# cmp_task K-fragment loads and select_row score-chunk loads issued up front instead of serialized load-wait chains; plus earlier P5/P7 epilogue restructures
# speedup vs baseline: 1.0293x; 1.0054x over previous
; #define MFMA32(a, b, c) __builtin_amdgcn_mfma_f32_32x32x16_bf16((a), (b), (c), 0, 0, 0)
; DI int crow(int r, int h) { return (r & 3) + 8 * (r >> 2) + 4 * h; }
; DI void cmp_task(const bf16_t* Z, const bf16_t* KCC, const bf16_t* VCT, bf16_t* OCMP, unsigned* selm, int b, int hk, int tg, int lane) {
;     const int r32 = lane & 31, h = lane >> 5;
;     const int tok = 8 * tg + (r32 >> 2), g = r32 & 3, head = hk * 4 + g;
;     const size_t grow = (size_t)b * SEQ + tok;
;     const bf16_t* zr = Z + grow * NZ;
;     bf16x8 qf[4];
; #pragma unroll
;     for (int s = 0; s < 4; ++s) qf[s] = *(const bf16x8*)(zr + ZC_QA + head * 64 + 16 * s + 8 * h);
;     const bf16_t* kc = KCC + (size_t)(b * 2 + hk) * 128 * 64; const bf16_t* vt = VCT + (size_t)(b * 2 + hk) * 64 * 128;
;     const int tmax = 8 * tg + 7;
;     const int nsub = tmax < 31 ? 0 : (((tmax - 31) >> 4) >> 5) + 1;
;     f32x16 p[4];
; #pragma unroll
;     for (int sub = 0; sub < 4; ++sub) {
;         if (sub < nsub) {
;             p[sub] = f16zero();
; #pragma unroll
;             for (int s = 0; s < 4; ++s) { const bf16x8 af = *(const bf16x8*)(kc + (size_t)(32 * sub + r32) * 64 + 16 * s + 8 * h); p[sub] = MFMA32(af, qf[s], p[sub]); }
; #pragma unroll
;             for (int r = 0; r < 16; ++r) { const int n = 32 * sub + crow(r, h); p[sub][r] = (16 * n + 31 <= tok) ? p[sub][r] * SM_C : NINF; }
;         } else {
.LBB0_481:
	s_mul_i32 s8, s63, s20
	s_add_i32 s9, s8, s92
	s_lshr_b32 s10, s9, 5
	s_and_b32 s10, s10, 0xc0
	s_add_i32 s10, s10, s9
	s_ashr_i32 s8, s9, 9
	s_and_b32 s54, s10, 0xff
	s_bfe_u32 s14, s9, 0x10008
	s_lshl_b32 s50, s54, 3
	s_ashr_i32 s9, s8, 31
	v_or_b32_e32 v131, s50, v113
	s_lshl_b64 s[10:11], s[8:9], 11
	v_or_b32_e32 v122, s10, v131
	v_mov_b64_e32 v[2:3], s[22:23]
	s_movk_i32 s9, 0x2200
	v_mad_u64_u32 v[2:3], s[48:49], v122, s9, v[2:3]
	v_lshl_or_b32 v1, s14, 8, v115
	v_mad_i32_i24 v3, s11, v244, v3
	v_lshlrev_b32_e32 v42, 1, v1
	v_lshl_add_u64 v[2:3], v[2:3], 0, v[42:43]
	v_mov_b32_e32 v41, v43
	v_lshl_add_u64 v[2:3], v[2:3], 0, v[40:41]
	global_load_dwordx4 v[30:33], v[2:3], off
	global_load_dwordx4 v[26:29], v[2:3], off offset:32
	global_load_dwordx4 v[22:25], v[2:3], off offset:64
	global_load_dwordx4 v[18:21], v[2:3], off offset:96
	s_lshl_b32 s8, s8, 1
	s_or_b32 s8, s8, s14
	s_ashr_i32 s9, s8, 31
	s_lshl_b64 s[8:9], s[8:9], 14
	s_or_b32 s10, s50, 7
	s_cmp_lt_u32 s10, 31
	s_cselect_b64 s[48:49], -1, 0
	s_cmp_gt_u32 s10, 30
	v_mov_b32_e32 v123, s11
	s_cselect_b64 s[10:11], -1, 0
	v_lshl_add_u64 v[124:125], v[44:45], 0, s[8:9]
	v_mov_b32_e32 v121, 0xff800000
	s_and_b64 vcc, exec, s[48:49]
	v_lshlrev_b32_e32 v126, 1, v38
	v_mov_b32_e32 v128, 0xff800000
	v_mov_b32_e32 v129, 0xff800000
	v_mov_b32_e32 v130, 0xff800000
	v_mov_b32_e32 v134, 0xff800000
	v_mov_b32_e32 v135, 0xff800000
	v_mov_b32_e32 v139, 0xff800000
	v_mov_b32_e32 v140, 0xff800000
	v_mov_b32_e32 v141, 0xff800000
	v_mov_b32_e32 v142, 0xff800000
	v_mov_b32_e32 v143, 0xff800000
	v_mov_b32_e32 v144, 0xff800000
	v_mov_b32_e32 v145, 0xff800000
	v_mov_b32_e32 v146, 0xff800000
	v_mov_b32_e32 v147, 0xff800000
	v_mov_b32_e32 v148, 0xff800000
	v_mov_b32_e32 v149, 0xff800000
	s_cbranch_vccnz .LBB0_483
	v_mov_b32_e32 v127, v43
	v_lshl_add_u64 v[94:95], v[124:125], 0, v[126:127]
	global_load_dwordx4 v[2:5], v[94:95], off
	global_load_dwordx4 v[140:143], v[94:95], off offset:32
	global_load_dwordx4 v[150:153], v[94:95], off offset:64
	global_load_dwordx4 v[154:157], v[94:95], off offset:96
	v_cmp_le_u32_e32 vcc, v46, v131
	s_waitcnt vmcnt(3)
	v_mfma_f32_32x32x16_bf16 v[2:17], v[2:5], v[30:33], 0
	s_waitcnt vmcnt(2)
	v_mfma_f32_32x32x16_bf16 v[2:17], v[140:143], v[26:29], v[2:17]
	s_waitcnt vmcnt(1)
	v_mfma_f32_32x32x16_bf16 v[2:17], v[150:153], v[22:25], v[2:17]
	s_waitcnt vmcnt(0)
	v_mfma_f32_32x32x16_bf16 v[2:17], v[154:157], v[18:21], v[2:17]
	s_nop 11
	v_pk_mul_f32 v[2:3], v[2:3], s[46:47] op_sel_hi:[1,0]
	s_nop 0
	v_cndmask_b32_e32 v128, v245, v2, vcc
	v_cmp_le_u32_e32 vcc, v37, v131
	v_mul_f32_e32 v1, 0x3e38aa3b, v4
	s_nop 0
	v_cndmask_b32_e32 v129, v245, v3, vcc
	v_cmp_le_u32_e32 vcc, v117, v131
	v_pk_mul_f32 v[2:3], v[6:7], s[46:47] op_sel_hi:[1,0]
	s_nop 0
	v_cndmask_b32_e32 v130, v245, v1, vcc
	v_mul_f32_e32 v1, 0x3e38aa3b, v5
	v_cmp_le_u32_e32 vcc, v119, v131
	s_nop 1
	v_cndmask_b32_e32 v134, v245, v1, vcc
	v_cmp_le_u32_e32 vcc, v48, v131
	v_mul_f32_e32 v1, 0x3e38aa3b, v8
	s_nop 0
	v_cndmask_b32_e32 v135, v245, v2, vcc
	v_cmp_le_u32_e32 vcc, v39, v131
	s_nop 1
	v_cndmask_b32_e32 v139, v245, v3, vcc
	v_cmp_le_u32_e32 vcc, v202, v131
	v_pk_mul_f32 v[2:3], v[10:11], s[46:47] op_sel_hi:[1,0]
	s_nop 0
	v_cndmask_b32_e32 v140, v245, v1, vcc
	v_mul_f32_e32 v1, 0x3e38aa3b, v9
	v_cmp_le_u32_e32 vcc, v203, v131
	s_nop 1
	v_cndmask_b32_e32 v141, v245, v1, vcc
	v_cmp_le_u32_e32 vcc, v50, v131
	v_mul_f32_e32 v1, 0x3e38aa3b, v12
	s_nop 0
	v_cndmask_b32_e32 v142, v245, v2, vcc
	v_cmp_le_u32_e32 vcc, v47, v131
	s_nop 1
	v_cndmask_b32_e32 v143, v245, v3, vcc
	v_cmp_le_u32_e32 vcc, v204, v131
	v_pk_mul_f32 v[2:3], v[14:15], s[46:47] op_sel_hi:[1,0]
	s_nop 0
	v_cndmask_b32_e32 v144, v245, v1, vcc
	v_mul_f32_e32 v1, 0x3e38aa3b, v13
	v_cmp_le_u32_e32 vcc, v205, v131
	s_nop 1
	v_cndmask_b32_e32 v145, v245, v1, vcc
	v_cmp_le_u32_e32 vcc, v52, v131
	v_mul_f32_e32 v1, 0x3e38aa3b, v16
	s_nop 0
	v_cndmask_b32_e32 v146, v245, v2, vcc
	v_cmp_le_u32_e32 vcc, v49, v131
	s_nop 1
	v_cndmask_b32_e32 v147, v245, v3, vcc
	v_cmp_le_u32_e32 vcc, v206, v131
	s_nop 1
	v_cndmask_b32_e32 v148, v245, v1, vcc
	v_mul_f32_e32 v1, 0x3e38aa3b, v17
	v_cmp_le_u32_e32 vcc, v207, v131
	s_nop 1
	v_cndmask_b32_e32 v149, v245, v1, vcc
.LBB0_483:
	s_sub_i32 s50, s50, 24
	s_lshr_b32 s50, s50, 9
	s_add_i32 s50, s50, 1
	s_and_b64 s[48:49], exec, s[48:49]
	s_cselect_b32 s55, 0, s50
	s_cmp_gt_u32 s55, 1
	s_cselect_b64 s[48:49], -1, 0
	s_cmp_lt_u32 s55, 2
	v_mov_b32_e32 v150, 0xff800000
	v_mov_b32_e32 v151, 0xff800000
	v_mov_b32_e32 v152, 0xff800000
	v_mov_b32_e32 v153, 0xff800000
	v_mov_b32_e32 v154, 0xff800000
	v_mov_b32_e32 v155, 0xff800000
	v_mov_b32_e32 v156, 0xff800000
	v_mov_b32_e32 v157, 0xff800000
	v_mov_b32_e32 v158, 0xff800000
	v_mov_b32_e32 v159, 0xff800000
	v_mov_b32_e32 v160, 0xff800000
	v_mov_b32_e32 v161, 0xff800000
	v_mov_b32_e32 v162, 0xff800000
	v_mov_b32_e32 v163, 0xff800000
	v_mov_b32_e32 v164, 0xff800000
	s_cbranch_scc1 .LBB0_485
; #define MFMA32(a, b, c) __builtin_amdgcn_mfma_f32_32x32x16_bf16((a), (b), (c), 0, 0, 0)
; DI int crow(int r, int h) { return (r & 3) + 8 * (r >> 2) + 4 * h; }
; DI void cmp_task(const bf16_t* Z, const bf16_t* KCC, const bf16_t* VCT, bf16_t* OCMP, unsigned* selm, int b, int hk, int tg, int lane) {
;     ...
;     for (int sub = 0; sub < 4; ++sub) {
;         if (sub < nsub) {
;             p[sub] = f16zero();
; #pragma unroll
;             for (int s = 0; s < 4; ++s) { const bf16x8 af = *(const bf16x8*)(kc + (size_t)(32 * sub + r32) * 64 + 16 * s + 8 * h); p[sub] = MFMA32(af, qf[s], p[sub]); }
; #pragma unroll
;             for (int r = 0; r < 16; ++r) { const int n = 32 * sub + crow(r, h); p[sub][r] = (16 * n + 31 <= tok) ? p[sub][r] * SM_C : NINF; }
;         } else {
	v_mov_b32_e32 v127, v43
	v_lshl_add_u64 v[2:3], v[124:125], 0, v[126:127]
	v_add_co_u32_e32 v94, vcc, 0x1000, v2
	s_nop 1
	v_addc_co_u32_e32 v95, vcc, 0, v3, vcc
	global_load_dwordx4 v[2:5], v[94:95], off
	global_load_dwordx4 v[150:153], v[94:95], off offset:32
	global_load_dwordx4 v[154:157], v[94:95], off offset:64
	global_load_dwordx4 v[158:161], v[94:95], off offset:96
	v_cmp_le_u32_e32 vcc, v54, v131
	s_waitcnt vmcnt(3)
	v_mfma_f32_32x32x16_bf16 v[2:17], v[2:5], v[30:33], 0
	s_waitcnt vmcnt(2)
	v_mfma_f32_32x32x16_bf16 v[2:17], v[150:153], v[26:29], v[2:17]
	s_waitcnt vmcnt(1)
	v_mfma_f32_32x32x16_bf16 v[2:17], v[154:157], v[22:25], v[2:17]
	s_waitcnt vmcnt(0)
	v_mfma_f32_32x32x16_bf16 v[2:17], v[158:161], v[18:21], v[2:17]
	s_nop 11
	v_pk_mul_f32 v[2:3], v[2:3], s[46:47] op_sel_hi:[1,0]
	s_nop 0
	v_cndmask_b32_e32 v121, v245, v2, vcc
	v_cmp_le_u32_e32 vcc, v51, v131
	v_mul_f32_e32 v1, 0x3e38aa3b, v4
	s_nop 0
	v_cndmask_b32_e32 v150, v245, v3, vcc
	v_cmp_le_u32_e32 vcc, v208, v131
	v_pk_mul_f32 v[2:3], v[6:7], s[46:47] op_sel_hi:[1,0]
	s_nop 0
	v_cndmask_b32_e32 v151, v245, v1, vcc
	v_mul_f32_e32 v1, 0x3e38aa3b, v5
	v_cmp_le_u32_e32 vcc, v209, v131
	s_nop 1
	v_cndmask_b32_e32 v152, v245, v1, vcc
	v_cmp_le_u32_e32 vcc, v56, v131
	v_mul_f32_e32 v1, 0x3e38aa3b, v8
	s_nop 0
	v_cndmask_b32_e32 v153, v245, v2, vcc
	v_cmp_le_u32_e32 vcc, v53, v131
	s_nop 1
	v_cndmask_b32_e32 v154, v245, v3, vcc
	v_cmp_le_u32_e32 vcc, v210, v131
	v_pk_mul_f32 v[2:3], v[10:11], s[46:47] op_sel_hi:[1,0]
	s_nop 0
	v_cndmask_b32_e32 v155, v245, v1, vcc
	v_mul_f32_e32 v1, 0x3e38aa3b, v9
	v_cmp_le_u32_e32 vcc, v211, v131
	s_nop 1
	v_cndmask_b32_e32 v156, v245, v1, vcc
	v_cmp_le_u32_e32 vcc, v58, v131
	v_mul_f32_e32 v1, 0x3e38aa3b, v12
	s_nop 0
	v_cndmask_b32_e32 v157, v245, v2, vcc
	v_cmp_le_u32_e32 vcc, v55, v131
	s_nop 1
	v_cndmask_b32_e32 v158, v245, v3, vcc
	v_cmp_le_u32_e32 vcc, v212, v131
	v_pk_mul_f32 v[2:3], v[14:15], s[46:47] op_sel_hi:[1,0]
	s_nop 0
	v_cndmask_b32_e32 v159, v245, v1, vcc
	v_mul_f32_e32 v1, 0x3e38aa3b, v13
	v_cmp_le_u32_e32 vcc, v213, v131
	s_nop 1
	v_cndmask_b32_e32 v160, v245, v1, vcc
	v_cmp_le_u32_e32 vcc, v60, v131
	v_mul_f32_e32 v1, 0x3e38aa3b, v16
	s_nop 0
	v_cndmask_b32_e32 v161, v245, v2, vcc
	v_cmp_le_u32_e32 vcc, v57, v131
	s_nop 1
	v_cndmask_b32_e32 v162, v245, v3, vcc
	v_cmp_le_u32_e32 vcc, v216, v131
	s_nop 1
	v_cndmask_b32_e32 v163, v245, v1, vcc
	v_mul_f32_e32 v1, 0x3e38aa3b, v17
	v_cmp_le_u32_e32 vcc, v217, v131
	s_nop 1
	v_cndmask_b32_e32 v164, v245, v1, vcc
.LBB0_485:
	s_cmp_gt_u32 s55, 2
	v_mov_b32_e32 v165, 0xff800000
	s_cselect_b64 s[50:51], -1, 0
	s_cmp_lt_u32 s55, 3
	v_mov_b32_e32 v166, 0xff800000
	v_mov_b32_e32 v167, 0xff800000
	v_mov_b32_e32 v174, 0xff800000
	v_mov_b32_e32 v175, 0xff800000
	v_mov_b32_e32 v190, 0xff800000
	v_mov_b32_e32 v191, 0xff800000
	v_mov_b32_e32 v192, 0xff800000
	v_mov_b32_e32 v193, 0xff800000
	v_mov_b32_e32 v194, 0xff800000
	v_mov_b32_e32 v195, 0xff800000
	v_mov_b32_e32 v196, 0xff800000
	v_mov_b32_e32 v197, 0xff800000
	v_mov_b32_e32 v247, 0xff800000
	v_mov_b32_e32 v248, 0xff800000
	v_mov_b32_e32 v249, 0xff800000
	v_mov_b32_e32 v250, 0xff800000
	s_cbranch_scc1 .LBB0_487
	v_mov_b32_e32 v127, v43
	v_lshl_add_u64 v[2:3], v[124:125], 0, v[126:127]
	v_add_co_u32_e32 v94, vcc, 0x2000, v2
	s_nop 1
	v_addc_co_u32_e32 v95, vcc, 0, v3, vcc
	global_load_dwordx4 v[2:5], v[94:95], off
	global_load_dwordx4 v[166:169], v[94:95], off offset:32
	global_load_dwordx4 v[170:173], v[94:95], off offset:64
	global_load_dwordx4 v[176:179], v[94:95], off offset:96
	v_cmp_le_u32_e32 vcc, v62, v131
	s_waitcnt vmcnt(3)
	v_mfma_f32_32x32x16_bf16 v[2:17], v[2:5], v[30:33], 0
	s_waitcnt vmcnt(2)
	v_mfma_f32_32x32x16_bf16 v[2:17], v[166:169], v[26:29], v[2:17]
	s_waitcnt vmcnt(1)
	v_mfma_f32_32x32x16_bf16 v[2:17], v[170:173], v[22:25], v[2:17]
	s_waitcnt vmcnt(0)
	v_mfma_f32_32x32x16_bf16 v[2:17], v[176:179], v[18:21], v[2:17]
	s_nop 11
	v_pk_mul_f32 v[2:3], v[2:3], s[46:47] op_sel_hi:[1,0]
	s_nop 0
	v_cndmask_b32_e32 v166, v245, v2, vcc
	v_cmp_le_u32_e32 vcc, v59, v131
	v_mul_f32_e32 v1, 0x3e38aa3b, v4
	s_nop 0
	v_cndmask_b32_e32 v167, v245, v3, vcc
	v_cmp_le_u32_e32 vcc, v218, v131
	v_pk_mul_f32 v[2:3], v[6:7], s[46:47] op_sel_hi:[1,0]
	s_nop 0
	v_cndmask_b32_e32 v174, v245, v1, vcc
	v_mul_f32_e32 v1, 0x3e38aa3b, v5
	v_cmp_le_u32_e32 vcc, v219, v131
	s_nop 1
	v_cndmask_b32_e32 v175, v245, v1, vcc
	v_cmp_le_u32_e32 vcc, v64, v131
	v_mul_f32_e32 v1, 0x3e38aa3b, v8
	s_nop 0
	v_cndmask_b32_e32 v190, v245, v2, vcc
	v_cmp_le_u32_e32 vcc, v61, v131
	s_nop 1
	v_cndmask_b32_e32 v191, v245, v3, vcc
	v_cmp_le_u32_e32 vcc, v220, v131
	v_pk_mul_f32 v[2:3], v[10:11], s[46:47] op_sel_hi:[1,0]
	s_nop 0
	v_cndmask_b32_e32 v192, v245, v1, vcc
	v_mul_f32_e32 v1, 0x3e38aa3b, v9
	v_cmp_le_u32_e32 vcc, v221, v131
	s_nop 1
	v_cndmask_b32_e32 v193, v245, v1, vcc
	v_cmp_le_u32_e32 vcc, v66, v131
	v_mul_f32_e32 v1, 0x3e38aa3b, v12
	s_nop 0
	v_cndmask_b32_e32 v194, v245, v2, vcc
	v_cmp_le_u32_e32 vcc, v63, v131
	s_nop 1
	v_cndmask_b32_e32 v195, v245, v3, vcc
	v_cmp_le_u32_e32 vcc, v222, v131
	v_pk_mul_f32 v[2:3], v[14:15], s[46:47] op_sel_hi:[1,0]
	s_nop 0
	v_cndmask_b32_e32 v196, v245, v1, vcc
	v_mul_f32_e32 v1, 0x3e38aa3b, v13
	v_cmp_le_u32_e32 vcc, v223, v131
	s_nop 1
	v_cndmask_b32_e32 v197, v245, v1, vcc
	v_cmp_le_u32_e32 vcc, v68, v131
	v_mul_f32_e32 v1, 0x3e38aa3b, v16
	s_nop 0
	v_cndmask_b32_e32 v247, v245, v2, vcc
	v_cmp_le_u32_e32 vcc, v65, v131
	s_nop 1
	v_cndmask_b32_e32 v248, v245, v3, vcc
	v_cmp_le_u32_e32 vcc, v224, v131
	s_nop 1
	v_cndmask_b32_e32 v249, v245, v1, vcc
	v_mul_f32_e32 v1, 0x3e38aa3b, v17
	v_cmp_le_u32_e32 vcc, v225, v131
	s_nop 1
	v_cndmask_b32_e32 v250, v245, v1, vcc
; #define MFMA32(a, b, c) __builtin_amdgcn_mfma_f32_32x32x16_bf16((a), (b), (c), 0, 0, 0)
; DI int crow(int r, int h) { return (r & 3) + 8 * (r >> 2) + 4 * h; }
; DI void cmp_task(const bf16_t* Z, const bf16_t* KCC, const bf16_t* VCT, bf16_t* OCMP, unsigned* selm, int b, int hk, int tg, int lane) {
;     ...
;     for (int sub = 0; sub < 4; ++sub) {
;         if (sub < nsub) {
;             p[sub] = f16zero();
; #pragma unroll
;             for (int s = 0; s < 4; ++s) { const bf16x8 af = *(const bf16x8*)(kc + (size_t)(32 * sub + r32) * 64 + 16 * s + 8 * h); p[sub] = MFMA32(af, qf[s], p[sub]); }
; #pragma unroll
;             for (int r = 0; r < 16; ++r) { const int n = 32 * sub + crow(r, h); p[sub][r] = (16 * n + 31 <= tok) ? p[sub][r] * SM_C : NINF; }
;         } else {
.LBB0_487:
	s_cmp_gt_u32 s55, 3
	s_cselect_b64 s[52:53], -1, 0
	s_cmp_lt_u32 s55, 4
	v_mov_b32_e32 v127, 0xff800000
	v_mov_b32_e32 v251, 0xff800000
	v_mov_b32_e32 v252, 0xff800000
	v_mov_b32_e32 v215, 0xff800000
	v_mov_b32_e32 v34, 0xff800000
	v_mov_b32_e32 v137, 0xff800000
	v_mov_b32_e32 v1, 0xff800000
	v_mov_b32_e32 v234, 0xff800000
	v_mov_b32_e32 v75, 0xff800000
	v_mov_b32_e32 v82, 0xff800000
	v_mov_b32_e32 v77, 0xff800000
	v_mov_b32_e32 v14, 0xff800000
	v_mov_b32_e32 v15, 0xff800000
	v_mov_b32_e32 v16, 0xff800000
	v_mov_b32_e32 v17, 0xff800000
	s_cbranch_scc1 .LBB0_489
	v_mov_b32_e32 v127, v43
	v_lshl_add_u64 v[2:3], v[124:125], 0, v[126:127]
	v_add_co_u32_e32 v94, vcc, 0x3000, v2
	s_nop 1
	v_addc_co_u32_e32 v95, vcc, 0, v3, vcc
	global_load_dwordx4 v[2:5], v[94:95], off
	global_load_dwordx4 v[168:171], v[94:95], off offset:32
	global_load_dwordx4 v[176:179], v[94:95], off offset:64
	global_load_dwordx4 v[180:183], v[94:95], off offset:96
	v_cmp_le_u32_e32 vcc, v70, v131
	s_waitcnt vmcnt(3)
	v_mfma_f32_32x32x16_bf16 v[2:17], v[2:5], v[30:33], 0
	s_waitcnt vmcnt(2)
	v_mfma_f32_32x32x16_bf16 v[2:17], v[168:171], v[26:29], v[2:17]
	s_waitcnt vmcnt(1)
	v_mfma_f32_32x32x16_bf16 v[2:17], v[176:179], v[22:25], v[2:17]
	s_waitcnt vmcnt(0)
	v_mfma_f32_32x32x16_bf16 v[2:17], v[180:183], v[18:21], v[2:17]
	s_nop 11
	v_pk_mul_f32 v[2:3], v[2:3], s[46:47] op_sel_hi:[1,0]
	s_nop 0
	v_cndmask_b32_e32 v165, v245, v2, vcc
	v_cmp_le_u32_e32 vcc, v67, v131
	v_mul_f32_e32 v1, 0x3e38aa3b, v4
	s_nop 0
	v_cndmask_b32_e32 v127, v245, v3, vcc
	v_cmp_le_u32_e32 vcc, v226, v131
	v_pk_mul_f32 v[2:3], v[6:7], s[46:47] op_sel_hi:[1,0]
	s_nop 0
	v_cndmask_b32_e32 v251, v245, v1, vcc
	v_mul_f32_e32 v1, 0x3e38aa3b, v5
	v_cmp_le_u32_e32 vcc, v227, v131
	s_nop 1
	v_cndmask_b32_e32 v252, v245, v1, vcc
	v_cmp_le_u32_e32 vcc, v72, v131
	v_mul_f32_e32 v1, 0x3e38aa3b, v8
	s_nop 0
	v_cndmask_b32_e32 v215, v245, v2, vcc
	v_cmp_le_u32_e32 vcc, v69, v131
	s_nop 1
	v_cndmask_b32_e32 v34, v245, v3, vcc
	v_cmp_le_u32_e32 vcc, v228, v131
	v_pk_mul_f32 v[2:3], v[10:11], s[46:47] op_sel_hi:[1,0]
	s_nop 0
	v_cndmask_b32_e32 v137, v245, v1, vcc
	v_mul_f32_e32 v1, 0x3e38aa3b, v9
	v_cmp_le_u32_e32 vcc, v229, v131
	s_nop 1
	v_cndmask_b32_e32 v1, v245, v1, vcc
	v_cmp_le_u32_e32 vcc, v74, v131
	s_nop 1
	v_cndmask_b32_e32 v234, v245, v2, vcc
	v_cmp_le_u32_e32 vcc, v71, v131
	v_mul_f32_e32 v2, 0x3e38aa3b, v12
	s_nop 0
	v_cndmask_b32_e32 v75, v245, v3, vcc
	v_cmp_le_u32_e32 vcc, v230, v131
	s_nop 1
	v_cndmask_b32_e32 v82, v245, v2, vcc
	v_mul_f32_e32 v2, 0x3e38aa3b, v13
	v_cmp_le_u32_e32 vcc, v231, v131
	s_nop 1
	v_cndmask_b32_e32 v77, v245, v2, vcc
	v_pk_mul_f32 v[2:3], v[14:15], s[46:47] op_sel_hi:[1,0]
	v_cmp_le_u32_e32 vcc, v76, v131
	s_nop 1
	v_cndmask_b32_e32 v14, v245, v2, vcc
	v_cmp_le_u32_e32 vcc, v73, v131
	v_mul_f32_e32 v2, 0x3e38aa3b, v16
	s_nop 0
	v_cndmask_b32_e32 v15, v245, v3, vcc
	v_cmp_le_u32_e32 vcc, v232, v131
	s_nop 1
	v_cndmask_b32_e32 v16, v245, v2, vcc
	v_mul_f32_e32 v2, 0x3e38aa3b, v17
	v_cmp_le_u32_e32 vcc, v233, v131
	s_nop 1
	v_cndmask_b32_e32 v17, v245, v2, vcc

; DI size_t sc_rowoff(int b, int t) { const int c = t >> 6; return (size_t)b * SC_PB + (size_t)4096 * (c * (c + 1) / 2) + (size_t)(t & 63) * (64 * (c + 1)); }
; DI void select_row(const float* SC, unsigned* dmask, int b, int t, int lane) {
;     unsigned* dm = dmask + ((size_t)b * SEQ + t) * 64;
;     const int nvalid = t + 1;
;     if (nvalid <= 256) {
;         const int w = lane;
;         const int lo = 32 * w; unsigned bits = 0u;
;         if (lo + 31 <= t) bits = 0xffffffffu; else if (lo <= t) bits = (2u << (t - lo)) - 1u;
;         dm[w] = bits; return;
;     }
;     const int nch = (nvalid + 255) >> 8;
;     const float* srow = SC + sc_rowoff(b, t) + 4 * lane;
;     unsigned u[8][4];
; #pragma unroll
;     for (int k = 0; k < 8; ++k) {
;         if (k < nch) {
;             const f32x4 v = *(const f32x4*)(srow + 256 * k);
; #pragma unroll
;             for (int e = 0; e < 4; ++e) { const unsigned bits = __builtin_bit_cast(unsigned, v[e] + 0.0f); const unsigned key = ((int)bits < 0) ? ~bits : (bits | 0x80000000u);
;                 u[k][e] = (256 * k + 4 * lane + e <= t) ? key : 0u; }
;         } else { u[k][0] = 0u; u[k][1] = 0u; u[k][2] = 0u; u[k][3] = 0u; }
;     }
.LBB0_535:
	s_and_b64 vcc, exec, s[76:77]
	s_cbranch_vccnz .LBB0_476
	s_mul_i32 s11, s64, s20
	s_add_i32 s11, s11, s92
	s_and_b32 s10, s11, 15
	s_ashr_i32 s65, s11, 4
	s_lshl_b32 s8, s10, 11
	s_ashr_i32 s9, s65, 31
	s_add_u32 s8, s8, s65
	s_addc_u32 s9, 0, s9
	s_lshl_b64 s[8:9], s[8:9], 8
	s_add_u32 s48, s21, s8
	s_addc_u32 s49, s68, s9
	s_cmpk_gt_i32 s65, 0xff
	s_mov_b64 s[8:9], -1
	s_cbranch_scc0 .LBB0_657
	s_lshr_b32 s8, s65, 6
	s_add_i32 s9, s8, 1
	s_mul_i32 s8, s9, s8
	s_lshr_b32 s14, s8, 1
	s_bfe_u32 s8, s11, 0x60004
	s_lshl_b32 s11, s9, 6
	s_mul_hi_u32 s9, s11, s8
	s_mul_i32 s8, s11, s8
	s_lshl_b64 s[8:9], s[8:9], 2
	s_add_u32 s8, s44, s8
	s_addc_u32 s9, s45, s9
	s_mul_i32 s10, s10, 0x840000
	s_add_u32 s10, s8, s10
	s_addc_u32 s11, s9, 0
	s_lshl_b64 s[8:9], s[14:15], 14
	s_add_u32 s8, s10, s8
	s_addc_u32 s9, s11, s9
	global_load_dwordx4 v[6:9], v120, s[8:9]
	global_load_dwordx4 v[2:5], v120, s[8:9] offset:1024
	s_add_u32 s98, s8, 0x1000
	s_addc_u32 s99, s9, 0
	s_cmpk_lt_u32 s65, 0x200
	s_cbranch_scc1 .Lsel_pf_done
	global_load_dwordx4 v[150:153], v120, s[8:9] offset:2048
	s_cmpk_lt_u32 s65, 0x300
	s_cbranch_scc1 .Lsel_pf_done
	global_load_dwordx4 v[154:157], v120, s[8:9] offset:3072
	s_cmpk_lt_u32 s65, 0x400
	s_cbranch_scc1 .Lsel_pf_done
	global_load_dwordx4 v[158:161], v120, s[98:99]
	s_cmpk_lt_u32 s65, 0x500
	s_cbranch_scc1 .Lsel_pf_done
	global_load_dwordx4 v[162:165], v120, s[98:99] offset:1024
	s_cmpk_lt_u32 s65, 0x600
	s_cbranch_scc1 .Lsel_pf_done
	global_load_dwordx4 v[166:169], v120, s[98:99] offset:2048
	s_cmpk_lt_u32 s65, 0x700
	s_cbranch_scc1 .Lsel_pf_done
	global_load_dwordx4 v[170:173], v120, s[98:99] offset:3072
.Lsel_pf_done:
	v_mov_b32_e32 v121, v43
	s_cmpk_gt_u32 s65, 0x1ff
	v_lshl_add_u64 v[10:11], s[8:9], 0, v[120:121]
	v_mov_b32_e32 v28, 0
	s_cselect_b64 s[10:11], -1, 0
	s_cmpk_lt_u32 s65, 0x200
	v_mov_b32_e32 v32, 0
	v_mov_b32_e32 v42, 0
	v_mov_b32_e32 v33, 0
	v_mov_b32_e32 v41, 0
	s_cbranch_scc1 .LBB0_539
	s_waitcnt vmcnt(0)
	v_mov_b64_e32 v[12:13], v[150:151]
	v_mov_b64_e32 v[14:15], v[152:153]
	v_pk_add_f32 v[12:13], v[12:13], 0 op_sel_hi:[1,0]
	s_nop 0
	v_and_b32_e32 v17, 0x7fffffff, v13
	v_and_b32_e32 v16, 0x7fffffff, v12
	v_pk_add_f32 v[14:15], v[14:15], 0 op_sel_hi:[1,0]
	v_xor_b32_e32 v1, -1, v13
	v_pk_add_f32 v[16:17], v[16:17], 0 neg_lo:[1,1] neg_hi:[1,1]
	v_cmp_gt_i32_e32 vcc, 0, v13
	v_xor_b32_e32 v20, -1, v12
	v_and_b32_e32 v19, 0x7fffffff, v15
	v_and_b32_e32 v18, 0x7fffffff, v14
	v_cndmask_b32_e32 v1, v17, v1, vcc
	v_cmp_gt_i32_e32 vcc, 0, v12
	v_xor_b32_e32 v21, -1, v15
	v_pk_add_f32 v[18:19], v[18:19], 0 neg_lo:[1,1] neg_hi:[1,1]
	v_cndmask_b32_e32 v12, v16, v20, vcc
	v_cmp_gt_i32_e32 vcc, 0, v15
	v_xor_b32_e32 v22, -1, v14
	s_nop 0
	v_cndmask_b32_e32 v13, v19, v21, vcc
	v_cmp_gt_i32_e32 vcc, 0, v14
	s_nop 1
	v_cndmask_b32_e32 v14, v18, v22, vcc
	v_cmp_ge_u32_e32 vcc, s65, v86
	s_nop 1
	v_cndmask_b32_e32 v33, 0, v12, vcc
	v_cmp_ge_u32_e32 vcc, s65, v87
	v_or_b32_e32 v12, 0x202, v88
	s_nop 0
	v_cndmask_b32_e32 v41, 0, v1, vcc
	v_cmp_ge_u32_e32 vcc, s65, v12
	s_nop 1
	v_cndmask_b32_e32 v32, 0, v14, vcc
	v_cmp_ge_u32_e32 vcc, s65, v89
	s_nop 1
	v_cndmask_b32_e32 v42, 0, v13, vcc
.LBB0_539:
	s_cmpk_gt_u32 s65, 0x2ff
	s_cselect_b64 s[54:55], -1, 0
	s_cmpk_lt_u32 s65, 0x300
	v_mov_b32_e32 v31, 0
	v_mov_b32_e32 v29, 0
	v_mov_b32_e32 v30, 0
	s_cbranch_scc1 .LBB0_541
	s_waitcnt vmcnt(0)
	v_mov_b64_e32 v[12:13], v[154:155]
	v_mov_b64_e32 v[14:15], v[156:157]
	v_pk_add_f32 v[12:13], v[12:13], 0 op_sel_hi:[1,0]
	s_nop 0
	v_and_b32_e32 v17, 0x7fffffff, v13
	v_and_b32_e32 v16, 0x7fffffff, v12
	v_pk_add_f32 v[14:15], v[14:15], 0 op_sel_hi:[1,0]
	v_xor_b32_e32 v1, -1, v13
	v_pk_add_f32 v[16:17], v[16:17], 0 neg_lo:[1,1] neg_hi:[1,1]
	v_cmp_gt_i32_e32 vcc, 0, v13
	v_xor_b32_e32 v20, -1, v12
	v_and_b32_e32 v19, 0x7fffffff, v15
	v_and_b32_e32 v18, 0x7fffffff, v14
	v_cndmask_b32_e32 v1, v17, v1, vcc
	v_cmp_gt_i32_e32 vcc, 0, v12
	v_xor_b32_e32 v21, -1, v15
	v_pk_add_f32 v[18:19], v[18:19], 0 neg_lo:[1,1] neg_hi:[1,1]
	v_cndmask_b32_e32 v12, v16, v20, vcc
	v_cmp_gt_i32_e32 vcc, 0, v15
	v_xor_b32_e32 v22, -1, v14
	s_nop 0
	v_cndmask_b32_e32 v13, v19, v21, vcc
	v_cmp_gt_i32_e32 vcc, 0, v14
	s_nop 1
	v_cndmask_b32_e32 v14, v18, v22, vcc
	v_cmp_ge_u32_e32 vcc, s65, v98
	s_nop 1
	v_cndmask_b32_e32 v29, 0, v12, vcc
	v_cmp_ge_u32_e32 vcc, s65, v91
	s_nop 1
	v_cndmask_b32_e32 v30, 0, v1, vcc
	v_cmp_ge_u32_e32 vcc, s65, v100
	s_nop 1
	v_cndmask_b32_e32 v28, 0, v14, vcc
	v_cmp_ge_u32_e32 vcc, s65, v93
	s_nop 1
	v_cndmask_b32_e32 v31, 0, v13, vcc
; DI void select_row(const float* SC, unsigned* dmask, int b, int t, int lane) {
;     ...
; #pragma unroll
;     for (int k = 0; k < 8; ++k) {
;         if (k < nch) {
;             const f32x4 v = *(const f32x4*)(srow + 256 * k);
; #pragma unroll
;             for (int e = 0; e < 4; ++e) { const unsigned bits = __builtin_bit_cast(unsigned, v[e] + 0.0f); const unsigned key = ((int)bits < 0) ? ~bits : (bits | 0x80000000u);
;                 u[k][e] = (256 * k + 4 * lane + e <= t) ? key : 0u; }
;         } else { u[k][0] = 0u; u[k][1] = 0u; u[k][2] = 0u; u[k][3] = 0u; }
;     }
.LBB0_541:
	s_cmpk_gt_u32 s65, 0x3ff
	v_mov_b32_e32 v18, 0
	s_cselect_b64 s[76:77], -1, 0
	s_cmpk_lt_u32 s65, 0x400
	v_mov_b32_e32 v26, 0
	v_mov_b32_e32 v27, 0
	v_mov_b32_e32 v24, 0
	v_mov_b32_e32 v25, 0
	s_cbranch_scc1 .LBB0_543
	v_add_co_u32_e32 v12, vcc, 0x1000, v10
	s_nop 1
	v_addc_co_u32_e32 v13, vcc, 0, v11, vcc
	s_waitcnt vmcnt(0)
	v_mov_b64_e32 v[12:13], v[158:159]
	v_mov_b64_e32 v[14:15], v[160:161]
	v_pk_add_f32 v[12:13], v[12:13], 0 op_sel_hi:[1,0]
	s_nop 0
	v_cmp_gt_i32_e32 vcc, 0, v12
	v_cmp_gt_i32_e64 s[8:9], 0, v13
	v_xor_b32_e32 v1, -1, v13
	v_xor_b32_e32 v16, -1, v12
	v_and_b32_e32 v13, 0x7fffffff, v13
	v_and_b32_e32 v12, 0x7fffffff, v12
	v_pk_add_f32 v[12:13], v[12:13], 0 neg_lo:[1,1] neg_hi:[1,1]
	s_nop 0
	v_cndmask_b32_e64 v1, v13, v1, s[8:9]
	v_cndmask_b32_e32 v12, v12, v16, vcc
	v_cmp_ge_u32_e32 vcc, s65, v102
	v_or_b32_e32 v13, 0x401, v88
	s_nop 0
	v_cndmask_b32_e32 v24, 0, v12, vcc
	v_cmp_ge_u32_e32 vcc, s65, v13
	v_pk_add_f32 v[12:13], v[14:15], 0 op_sel_hi:[1,0]
	s_nop 0
	v_cndmask_b32_e32 v25, 0, v1, vcc
	v_cmp_gt_i32_e32 vcc, 0, v12
	v_cmp_gt_i32_e64 s[8:9], 0, v13
	v_xor_b32_e32 v1, -1, v13
	v_xor_b32_e32 v14, -1, v12
	v_and_b32_e32 v13, 0x7fffffff, v13
	v_and_b32_e32 v12, 0x7fffffff, v12
	v_pk_add_f32 v[12:13], v[12:13], 0 neg_lo:[1,1] neg_hi:[1,1]
	s_nop 0
	v_cndmask_b32_e64 v1, v13, v1, s[8:9]
	v_cndmask_b32_e32 v12, v12, v14, vcc
	v_cmp_ge_u32_e32 vcc, s65, v104
	v_or_b32_e32 v13, 0x403, v88
	s_nop 0
	v_cndmask_b32_e32 v26, 0, v12, vcc
	v_cmp_ge_u32_e32 vcc, s65, v13
	s_nop 1
	v_cndmask_b32_e32 v27, 0, v1, vcc
.LBB0_543:
	s_cmpk_gt_u32 s65, 0x4ff
	s_cselect_b64 s[52:53], -1, 0
	s_cmpk_lt_u32 s65, 0x500
	v_mov_b32_e32 v23, 0
	v_mov_b32_e32 v21, 0
	v_mov_b32_e32 v22, 0
	s_cbranch_scc1 .LBB0_545
	v_add_co_u32_e32 v12, vcc, 0x1000, v10
	s_nop 1
	v_addc_co_u32_e32 v13, vcc, 0, v11, vcc
	s_waitcnt vmcnt(0)
	v_mov_b64_e32 v[12:13], v[162:163]
	v_mov_b64_e32 v[14:15], v[164:165]
	v_pk_add_f32 v[12:13], v[12:13], 0 op_sel_hi:[1,0]
	s_nop 0
	v_cmp_gt_i32_e32 vcc, 0, v12
	v_cmp_gt_i32_e64 s[8:9], 0, v13
	v_xor_b32_e32 v1, -1, v13
	v_xor_b32_e32 v16, -1, v12
	v_and_b32_e32 v13, 0x7fffffff, v13
	v_and_b32_e32 v12, 0x7fffffff, v12
	v_pk_add_f32 v[12:13], v[12:13], 0 neg_lo:[1,1] neg_hi:[1,1]
	s_nop 0
	v_cndmask_b32_e32 v12, v12, v16, vcc
	v_cmp_ge_u32_e32 vcc, s65, v106
	v_cndmask_b32_e64 v1, v13, v1, s[8:9]
	s_nop 0
	v_cndmask_b32_e32 v21, 0, v12, vcc
	v_cmp_ge_u32_e32 vcc, s65, v99
	v_pk_add_f32 v[12:13], v[14:15], 0 op_sel_hi:[1,0]
	s_nop 0
	v_cndmask_b32_e32 v22, 0, v1, vcc
	v_cmp_gt_i32_e32 vcc, 0, v12
	v_cmp_gt_i32_e64 s[8:9], 0, v13
	v_xor_b32_e32 v1, -1, v13
	v_xor_b32_e32 v14, -1, v12
	v_and_b32_e32 v13, 0x7fffffff, v13
	v_and_b32_e32 v12, 0x7fffffff, v12
	v_pk_add_f32 v[12:13], v[12:13], 0 neg_lo:[1,1] neg_hi:[1,1]
	s_nop 0
	v_cndmask_b32_e32 v12, v12, v14, vcc
	v_cmp_ge_u32_e32 vcc, s65, v108
	v_cndmask_b32_e64 v1, v13, v1, s[8:9]
	s_nop 0
	v_cndmask_b32_e32 v18, 0, v12, vcc
	v_cmp_ge_u32_e32 vcc, s65, v101
	s_nop 1
	v_cndmask_b32_e32 v23, 0, v1, vcc
.LBB0_545:
	s_cmpk_gt_u32 s65, 0x5ff
	v_mov_b32_e32 v12, 0
	s_cselect_b64 s[80:81], -1, 0
	s_cmpk_lt_u32 s65, 0x600
	v_mov_b32_e32 v19, 0
	v_mov_b32_e32 v20, 0
	v_mov_b32_e32 v15, 0
	v_mov_b32_e32 v16, 0
	s_cbranch_scc1 .LBB0_547
	v_add_co_u32_e32 v14, vcc, 0x1000, v10
	s_nop 1
	v_addc_co_u32_e32 v15, vcc, 0, v11, vcc
	s_waitcnt vmcnt(0)
	v_mov_b64_e32 v[94:95], v[166:167]
	v_mov_b64_e32 v[96:97], v[168:169]
	v_pk_add_f32 v[14:15], v[94:95], 0 op_sel_hi:[1,0]
	s_nop 0
	v_cmp_gt_i32_e32 vcc, 0, v14
	v_cmp_gt_i32_e64 s[8:9], 0, v15
	v_xor_b32_e32 v1, -1, v15
	v_xor_b32_e32 v13, -1, v14
	v_and_b32_e32 v15, 0x7fffffff, v15
	v_and_b32_e32 v14, 0x7fffffff, v14
	v_pk_add_f32 v[14:15], v[14:15], 0 neg_lo:[1,1] neg_hi:[1,1]
	v_pk_add_f32 v[34:35], v[96:97], 0 op_sel_hi:[1,0]
	v_cndmask_b32_e32 v13, v14, v13, vcc
	v_cmp_ge_u32_e32 vcc, s65, v110
	v_cndmask_b32_e64 v1, v15, v1, s[8:9]
	v_cmp_gt_i32_e64 s[8:9], 0, v35
	v_cndmask_b32_e32 v15, 0, v13, vcc
	v_cmp_ge_u32_e32 vcc, s65, v103
	v_xor_b32_e32 v13, -1, v34
	s_nop 0
	v_cndmask_b32_e32 v16, 0, v1, vcc
	v_cmp_gt_i32_e32 vcc, 0, v34
	v_xor_b32_e32 v1, -1, v35
	v_and_b32_e32 v35, 0x7fffffff, v35
	v_and_b32_e32 v34, 0x7fffffff, v34
	v_pk_add_f32 v[34:35], v[34:35], 0 neg_lo:[1,1] neg_hi:[1,1]
	s_nop 0
	v_cndmask_b32_e32 v13, v34, v13, vcc
	v_cmp_ge_u32_e32 vcc, s65, v112
	v_cndmask_b32_e64 v1, v35, v1, s[8:9]
	s_nop 0
	v_cndmask_b32_e32 v19, 0, v13, vcc
	v_cmp_ge_u32_e32 vcc, s65, v105
	s_nop 1
	v_cndmask_b32_e32 v20, 0, v1, vcc
.LBB0_547:
	s_cmpk_gt_u32 s65, 0x6ff
	s_cselect_b64 s[50:51], -1, 0
	s_cmpk_lt_u32 s65, 0x700
	v_mov_b32_e32 v17, 0
	v_mov_b32_e32 v13, 0
	v_mov_b32_e32 v14, 0
	s_cbranch_scc1 .LBB0_549
	v_add_co_u32_e32 v10, vcc, 0x1000, v10
	s_nop 1
	v_addc_co_u32_e32 v11, vcc, 0, v11, vcc
	s_waitcnt vmcnt(0)
	v_mov_b64_e32 v[94:95], v[170:171]
	v_mov_b64_e32 v[96:97], v[172:173]
	v_pk_add_f32 v[10:11], v[94:95], 0 op_sel_hi:[1,0]
	s_nop 0
	v_cmp_gt_i32_e32 vcc, 0, v10
	v_cmp_gt_i32_e64 s[8:9], 0, v11
	v_xor_b32_e32 v1, -1, v11
	v_xor_b32_e32 v12, -1, v10
	v_and_b32_e32 v11, 0x7fffffff, v11
	v_and_b32_e32 v10, 0x7fffffff, v10
	v_pk_add_f32 v[10:11], v[10:11], 0 neg_lo:[1,1] neg_hi:[1,1]
	s_nop 0
	v_cndmask_b32_e32 v10, v10, v12, vcc
	v_cmp_ge_u32_e32 vcc, s65, v114
	v_cndmask_b32_e64 v1, v11, v1, s[8:9]
	s_nop 0
	v_cndmask_b32_e32 v13, 0, v10, vcc
	v_cmp_ge_u32_e32 vcc, s65, v107
	v_pk_add_f32 v[10:11], v[96:97], 0 op_sel_hi:[1,0]
	s_nop 0
	v_cndmask_b32_e32 v14, 0, v1, vcc
	v_cmp_gt_i32_e32 vcc, 0, v10
	v_cmp_gt_i32_e64 s[8:9], 0, v11
	v_xor_b32_e32 v1, -1, v11
	v_xor_b32_e32 v12, -1, v10
	v_and_b32_e32 v11, 0x7fffffff, v11
	v_and_b32_e32 v10, 0x7fffffff, v10
	v_pk_add_f32 v[10:11], v[10:11], 0 neg_lo:[1,1] neg_hi:[1,1]
	s_nop 0
	v_cndmask_b32_e32 v10, v10, v12, vcc
	v_cmp_ge_u32_e32 vcc, s65, v116
	v_cndmask_b32_e64 v1, v11, v1, s[8:9]
	s_nop 0
	v_cndmask_b32_e32 v12, 0, v10, vcc
	v_cmp_ge_u32_e32 vcc, s65, v109
	s_nop 1
	v_cndmask_b32_e32 v17, 0, v1, vcc

; __global__ void __launch_bounds__(NTHR, 2) fwd_kernel(Args a) {
	.amdhsa_kernel _Z10fwd_kernel4Args
		.amdhsa_group_segment_fixed_size 0
		.amdhsa_private_segment_fixed_size 0
		.amdhsa_kernarg_size 408
		.amdhsa_user_sgpr_count 2
		.amdhsa_user_sgpr_dispatch_ptr 0
		.amdhsa_user_sgpr_queue_ptr 0
		.amdhsa_user_sgpr_kernarg_segment_ptr 1
		.amdhsa_user_sgpr_dispatch_id 0
		.amdhsa_user_sgpr_kernarg_preload_length 0
		.amdhsa_user_sgpr_kernarg_preload_offset 0
		.amdhsa_user_sgpr_private_segment_size 0
		.amdhsa_uses_dynamic_stack 0
		.amdhsa_enable_private_segment 0
		.amdhsa_system_sgpr_workgroup_id_x 1
		.amdhsa_system_sgpr_workgroup_id_y 0
		.amdhsa_system_sgpr_workgroup_id_z 0
		.amdhsa_system_sgpr_workgroup_info 0
		.amdhsa_system_vgpr_workitem_id 0
		.amdhsa_next_free_vgpr 256
		.amdhsa_next_free_sgpr 100
		.amdhsa_accum_offset 256
		.amdhsa_reserve_vcc 1
		.amdhsa_float_round_mode_32 0
		.amdhsa_float_round_mode_16_64 0
		.amdhsa_float_denorm_mode_32 3
		.amdhsa_float_denorm_mode_16_64 3
		.amdhsa_dx10_clamp 1
		.amdhsa_ieee_mode 1
		.amdhsa_fp16_overflow 0
		.amdhsa_tg_split 0
		.amdhsa_exception_fp_ieee_invalid_op 0
		.amdhsa_exception_fp_denorm_src 0
		.amdhsa_exception_fp_ieee_div_zero 0
		.amdhsa_exception_fp_ieee_overflow 0
		.amdhsa_exception_fp_ieee_underflow 0
		.amdhsa_exception_fp_ieee_inexact 0
		.amdhsa_exception_int_div_zero 0
	.end_amdhsa_kernel

; __global__ void __launch_bounds__(NTHR, 2) fwd_kernel(Args a) {
amdhsa.kernels:
  - .agpr_count:     0
    .args:
      - .offset:         0
        .size:           152
        .value_kind:     by_value
      - .offset:         152
        .size:           4
        .value_kind:     hidden_block_count_x
      - .offset:         156
        .size:           4
        .value_kind:     hidden_block_count_y
      - .offset:         160
        .size:           4
        .value_kind:     hidden_block_count_z
      - .offset:         164
        .size:           2
        .value_kind:     hidden_group_size_x
      - .offset:         166
        .size:           2
        .value_kind:     hidden_group_size_y
      - .offset:         168
        .size:           2
        .value_kind:     hidden_group_size_z
      - .offset:         170
        .size:           2
        .value_kind:     hidden_remainder_x
      - .offset:         172
        .size:           2
        .value_kind:     hidden_remainder_y
      - .offset:         174
        .size:           2
        .value_kind:     hidden_remainder_z
      - .offset:         192
        .size:           8
        .value_kind:     hidden_global_offset_x
      - .offset:         200
        .size:           8
        .value_kind:     hidden_global_offset_y
      - .offset:         208
        .size:           8
        .value_kind:     hidden_global_offset_z
      - .offset:         216
        .size:           2
        .value_kind:     hidden_grid_dims
      - .offset:         272
        .size:           4
        .value_kind:     hidden_dynamic_lds_size
    .group_segment_fixed_size: 0
    .kernarg_segment_align: 8
    .kernarg_segment_size: 408
    .language:       OpenCL C
    .language_version:
      - 2
      - 0
    .max_flat_workgroup_size: 512
    .name:           _Z10fwd_kernel4Args
    .private_segment_fixed_size: 0
    .sgpr_count:     106
    .sgpr_spill_count: 140
    .symbol:         _Z10fwd_kernel4Args.kd
    .uniform_work_group_size: 1
    .uses_dynamic_stack: false
    .vgpr_count:     256
    .vgpr_spill_count: 0
    .wavefront_size: 64
